# w_out phase: the split-K units of the sample rows run after the full tiles instead of before them
# baseline (speedup 1.0000x reference)
.LBB0_1450:
	s_cmp_lt_i32 s52, 5
	s_cselect_b64 s[2:3], -1, 0
	s_and_b64 s[0:1], s[2:3], s[0:1]
	s_andn2_b64 vcc, exec, s[0:1]
	s_mov_b32 s84, s60
	s_cbranch_vccnz .LBB0_1505
	v_cvt_f32_u32_e32 v2, s96
	s_cmpk_gt_i32 s96, 0x7f
	s_cselect_b64 s[2:3], -1, 0
	s_cmpk_lt_i32 s97, 0
	s_cselect_b64 s[4:5], -1, 0
	v_rcp_iflag_f32_e32 v10, v2
	s_and_b64 s[4:5], s[4:5], s[2:3]
	v_cndmask_b32_e64 v3, 0, 1, s[4:5]
	v_readfirstlane_b32 s14, v0
	v_cmp_ne_u32_e64 s[2:3], 1, v3
	s_andn2_b64 vcc, exec, s[4:5]
	s_mov_b32 s4, 0
	s_cbranch_vccnz .LBB0_1453
	v_mul_f32_e32 v2, 0x4f7ffffe, v10
	v_cvt_u32_f32_e32 v2, v2
	s_sub_i32 s4, 0, s96
	v_readfirstlane_b32 s5, v2
	s_mul_i32 s4, s4, s5
	s_mul_hi_u32 s4, s5, s4
	s_add_i32 s5, s5, s4
	s_lshr_b32 s4, s5, 23
	s_mul_i32 s4, s4, s96
	s_sub_i32 s4, 0x200, s4
	s_sub_i32 s5, s4, s96
	s_cmp_ge_u32 s4, s96
	s_cselect_b32 s4, s5, s4
	s_sub_i32 s5, s4, s96
	s_cmp_ge_u32 s4, s96
	s_cselect_b32 s4, s5, s4
	s_cmp_eq_u32 s4, 0
	s_cselect_b32 s4, 0x200, 0
